# adds: skip the grid barrier after the last layer's empty context-norm phase
# speedup vs baseline: 1.0406x; 1.0069x over previous
; __device__ __forceinline__ unsigned xb_ld(unsigned* p)              { return __hip_atomic_load(p, __ATOMIC_RELAXED, __HIP_MEMORY_SCOPE_AGENT); }
; __device__ __forceinline__ unsigned xb_add(unsigned* p, unsigned v) { return __hip_atomic_fetch_add(p, v, __ATOMIC_RELAXED, __HIP_MEMORY_SCOPE_AGENT); }
; #define XB_SPIN(cond, bar) do { unsigned _sp = 0; while (cond) { __builtin_amdgcn_s_sleep(1); \
;     if ((++_sp & 255u) == 0u) { if (xb_ld(&(bar)[XB_TMO])) break; if (_sp > XB_SPIN_CAP) { atomicAdd(&(bar)[XB_TMO], 1u); break; } } } } while (0)
; __device__ __forceinline__ int fresh_lane() { int t; asm volatile("v_mbcnt_lo_u32_b32 %0, -1, 0\n\tv_mbcnt_hi_u32_b32 %0, -1, %0" : "=v"(t)); return t; }
; __device__ __forceinline__ void xcd_barrier(const XcdBarrier& b, int tid) {
;     asm volatile("s_waitcnt vmcnt(0)" ::: "memory");
;     __syncthreads();
;     if (tid == 0) {
;         unsigned* bar = b.bar;
;         __builtin_amdgcn_s_waitcnt(0);
;         unsigned nloc = b.st[0], nx = b.st[1];
;         if (nloc == 0u) { xcd_barrier_complete(bar, b.x, nloc, nx); b.st[0] = nloc; b.st[1] = nx; }
;         const unsigned old = xb_add(&bar[XB_XSUB(b.x)], 1u);
;         const unsigned gen = old / nloc;
;         if (old + 1u == (gen + 1u) * nloc) {
;             __builtin_amdgcn_fence(__ATOMIC_RELEASE, "agent");
;             asm volatile("s_waitcnt vmcnt(0)" ::: "memory");
;             const unsigned og = xb_add(&bar[XB_TOP], 1u);
;             const unsigned tg = og / nx;
;             if (og + 1u == (tg + 1u) * nx) xb_add(&bar[XB_TOPGEN], 1u);
;             else XB_SPIN(xb_ld(&bar[XB_TOPGEN]) == tg, bar);
;             __builtin_amdgcn_fence(__ATOMIC_ACQUIRE, "agent");
;             xb_add(&bar[XB_XGEN(b.x)], 1u);
;             asm volatile("s_waitcnt vmcnt(0)" ::: "memory");
;         } else {
;             XB_SPIN(xb_ld(&bar[XB_XGEN(b.x)]) == gen, bar);
;             __builtin_amdgcn_fence(__ATOMIC_ACQUIRE, "agent");
;             asm volatile("s_waitcnt vmcnt(0)" ::: "memory");
;         }
;     }
;     __syncthreads();
; }
; __global__ void __launch_bounds__(NWAVES * 64, 2) mk_fwd(Args args) {
;     ...
;         if (ph + 1 < hi) xcd_barrier(bar, wave_s * 64 + fresh_lane());
.LBB0_909:
	v_mbcnt_lo_u32_b32 v0, -1, 0
	v_mbcnt_hi_u32_b32 v0, -1, v0
	s_waitcnt vmcnt(0)
	s_waitcnt vmcnt(0) lgkmcnt(0)
	v_sub_u32_e32 v0, 0, v0
	v_cmp_eq_u32_e32 vcc, s64, v0
	s_barrier
	s_cmp_eq_u32 s86, 35
	s_cselect_b32 s98, 0, -1
	s_and_b32 vcc_lo, vcc_lo, s98
	s_and_b32 vcc_hi, vcc_hi, s98
	s_and_saveexec_b64 s[0:1], vcc
	s_cbranch_execnz .LBB0_910
	s_getpc_b64 s[98:99]
